# barrier: leader invalidate moved off the TOP atomic wait (before first poll / behind the TOPGEN bump), unused XGEN bump dropped
# baseline (speedup 1.0000x reference)
.LBB0_663:
	s_or_b64 exec, exec, s[6:7]
	s_waitcnt vmcnt(0)
	v_readfirstlane_b32 s2, v3
	v_sub_u32_e32 v4, 0, v2
	s_mov_b64 s[6:7], -1
	v_add_u32_e32 v3, s2, v0
	v_cvt_f32_u32_e32 v0, v2
	v_readlane_b32 s2, v247, 19
	v_readlane_b32 s3, v247, 20
	v_rcp_iflag_f32_e32 v0, v0
	s_nop 0
	v_mul_f32_e32 v0, 0x4f7ffffe, v0
	v_cvt_u32_f32_e32 v0, v0
	v_mul_lo_u32 v4, v4, v0
	v_mul_hi_u32 v4, v0, v4
	v_add_u32_e32 v0, v0, v4
	v_mul_hi_u32 v0, v3, v0
	v_mul_lo_u32 v4, v0, v2
	v_sub_u32_e32 v4, v3, v4
	v_cmp_ge_u32_e32 vcc, v4, v2
	v_add_u32_e32 v5, 1, v0
	v_add_u32_e32 v3, 1, v3
	v_cndmask_b32_e32 v0, v0, v5, vcc
	v_sub_u32_e32 v5, v4, v2
	v_cndmask_b32_e32 v4, v4, v5, vcc
	v_cmp_ge_u32_e32 vcc, v4, v2
	v_add_u32_e32 v4, 1, v0
	s_nop 0
	v_cndmask_b32_e32 v0, v0, v4, vcc
	v_mul_lo_u32 v4, v2, v0
	v_add_u32_e32 v2, v4, v2
	v_cmp_ne_u32_e32 vcc, v3, v2
	v_mov_b64_e32 v[2:3], s[2:3]
	s_and_saveexec_b64 s[4:5], vcc
	s_cbranch_execz .LBB0_675
	v_readlane_b32 s2, v247, 19
	v_readlane_b32 s3, v247, 20
	s_mov_b64 s[8:9], 0
	s_nop 3
	buffer_inv sc1
	global_load_dword v2, v1, s[2:3] sc1
	s_waitcnt vmcnt(0)
	v_cmp_eq_u32_e32 vcc, v2, v0
	s_and_saveexec_b64 s[6:7], vcc
	s_cbranch_execz .LBB0_674
	s_mov_b32 s2, 1
	s_branch .LBB0_667

.LBB0_675:
	s_or_b64 exec, exec, s[4:5]
	s_and_saveexec_b64 s[4:5], s[6:7]
	s_cbranch_execz .LBB0_677
	global_atomic_add v[2:3], v189, off
	buffer_inv sc1

.LBB0_678:
	s_bcnt1_i32_b64 s2, s[4:5]
	v_mov_b32_e32 v0, s2
	v_readlane_b32 s2, v247, 15
	v_readlane_b32 s3, v247, 16
	s_nop 4
	s_getpc_b64 s[98:99]
